# LRU elementwise: bias add + scale folded into fma (pre-scaled biases), -8*softplus*log2e folded into one multiplier; redundant pads in the tile loops removed
# speedup vs baseline: 1.0068x; 1.0068x over previous
; template <bool FINAL>
; __device__ __forceinline__ void lru_item(const Ctx& C, int l, int item) {
;     ...
;                 for (int dt = 0; dt < 4; ++dt) {
;                     union { bf16x8 v; unsigned u[4]; } t_; t_.u[0] = cvt_pk_bf16(f[dt][0], f[dt][1]); t_.u[1] = cvt_pk_bf16(f[dt][2], f[dt][3]); t_.u[2] = cvt_pk_bf16(f[dt][4], f[dt][5]); t_.u[3] = cvt_pk_bf16(f[dt][6], f[dt][7]); Bw[ty][dt][ks] = t_.v; }
;                 asm volatile("" ::: "memory");
;             }
;     {
;         int ch = tid & 255; asm volatile("" : "+v"(ch)); const int hf = tid >> 8;
;         const float w0 = C.P->in[5][(l * 4 + 0) * 256 + ch], w1 = C.P->in[5][(l * 4 + 1) * 256 + ch], w2 = C.P->in[5][(l * 4 + 2) * 256 + ch], w3 = C.P->in[5][(l * 4 + 3) * 256 + ch], cb = C.P->in[6][l * 256 + ch];
;         const int tl0 = hf * 32, t0 = c * 64 + tl0;
;         const bf16_t* colp = pb + (size_t)(b * SEQ) * 512 + ch;
;         float xm2 = (t0 - 2 >= 0) ? bf2f(colp[(size_t)(t0 - 2) * 512]) : 0.f, xm1 = (t0 - 1 >= 0) ? bf2f(colp[(size_t)(t0 - 1) * 512]) : 0.f, x0 = bf2f(colp[(size_t)t0 * 512]);
; #pragma unroll 1
;         for (int k8 = 0; k8 < 4; ++k8) { float xn[8];
; #pragma unroll
;             for (int k = 0; k < 8; ++k) { const int t = t0 + k8 * 8 + k + 1; xn[k] = (t < SEQ) ? bf2f(colp[(size_t)t * 512]) : 0.f; }
; #pragma unroll
;             for (int k = 0; k < 8; ++k) { xc[(tl0 + k8 * 8 + k) * XCP + ch] = f2bf(cb + w0 * xm2 + w1 * xm1 + w2 * x0 + w3 * xn[k]); xm2 = xm1; xm1 = x0; x0 = xn[k]; } }
;     }
;     __syncthreads();
;     {
;         float bav[4], bxv[4], spv[4];
; #pragma unroll
;         for (int dt = 0; dt < 4; ++dt) { const int chd = n * 64 + 16 * dt + fr; bav[dt] = C.P->in[8][(l * 2 + z) * 256 + chd]; bxv[dt] = C.P->in[10][(l * 2 + z) * 256 + chd];
;             const float lam = C.P->in[11][(l * 2 + z) * 256 + chd]; spv[dt] = (-lam > 15.f) ? -lam : log1pf(__expf(-lam)); }
;         const size_t cidx = (size_t)((z * 8 + b) * 64 + c) * 256 + n * 64 + lane;
;         float h = FINAL ? C.fp(OFF_CARH)[cidx] : 0.f, Ap = 1.f;
;         bf16_t* Hz = z ? H1 : H0;
; #pragma unroll 1
;         for (int s4 = 0; s4 < 4; ++s4) { const int tt = z ? 3 - s4 : s4;
;             const bf16_t* xrow = xc + (16 * tt + fr) * XCP + n * 64 + 8 * quad;
;             const bf16x8 xa0 = *(const bf16x8*)xrow, xa1 = *(const bf16x8*)(xrow + 32);
; #pragma unroll
.LBB0_465:
	s_or_b64 exec, exec, s[0:1]
	v_cvt_pk_bf16_f32 v0, v6, v9
	v_cvt_pk_bf16_f32 v1, v28, v34
	v_cvt_pk_bf16_f32 v2, v40, v42
	v_cvt_pk_bf16_f32 v3, v48, v50
	v_cvt_pk_bf16_f32 v4, v7, v10
	v_cvt_pk_bf16_f32 v5, v20, v21
	v_cvt_pk_bf16_f32 v6, v36, v37
	v_cvt_pk_bf16_f32 v7, v44, v45
	v_cvt_pk_bf16_f32 v8, v8, v11
	v_cvt_pk_bf16_f32 v9, v16, v17
	v_cvt_pk_bf16_f32 v10, v22, v23
	v_cvt_pk_bf16_f32 v11, v38, v39
	v_cvt_pk_bf16_f32 v12, v13, v12
	v_cvt_pk_bf16_f32 v13, v15, v14
	v_cvt_pk_bf16_f32 v14, v19, v18
	v_cvt_pk_bf16_f32 v15, v29, v24
	v_cvt_pk_bf16_f32 v16, v25, v30
	v_cvt_pk_bf16_f32 v17, v60, v68
	v_cvt_pk_bf16_f32 v18, v74, v76
	v_cvt_pk_bf16_f32 v19, v102, v104
	v_cvt_pk_bf16_f32 v20, v26, v31
	v_cvt_pk_bf16_f32 v21, v52, v53
	v_cvt_pk_bf16_f32 v22, v70, v71
	v_cvt_pk_bf16_f32 v23, v98, v99
	v_cvt_pk_bf16_f32 v24, v27, v32
	v_cvt_pk_bf16_f32 v25, v46, v47
	v_cvt_pk_bf16_f32 v26, v54, v55
	v_cvt_pk_bf16_f32 v27, v72, v73
	v_cvt_pk_bf16_f32 v28, v35, v33
	v_cvt_pk_bf16_f32 v29, v43, v41
	v_cvt_pk_bf16_f32 v30, v51, v49
	v_cvt_pk_bf16_f32 v31, v61, v56
	v_cvt_pk_bf16_f32 v32, v57, v62
	v_cvt_pk_bf16_f32 v33, v174, v194
	v_cvt_pk_bf16_f32 v34, v200, v202
	v_cvt_pk_bf16_f32 v35, v208, v210
	v_cvt_pk_bf16_f32 v36, v58, v63
	v_cvt_pk_bf16_f32 v37, v166, v167
	v_cvt_pk_bf16_f32 v38, v196, v197
	v_cvt_pk_bf16_f32 v39, v204, v205
	v_cvt_pk_bf16_f32 v40, v59, v66
	v_cvt_pk_bf16_f32 v41, v100, v101
	v_cvt_pk_bf16_f32 v42, v168, v169
	v_cvt_pk_bf16_f32 v43, v198, v199
	v_cvt_pk_bf16_f32 v44, v69, v67
	v_cvt_pk_bf16_f32 v45, v77, v75
	v_cvt_pk_bf16_f32 v46, v105, v103
	v_cvt_pk_bf16_f32 v47, v175, v170
	v_cvt_pk_bf16_f32 v48, v171, v176
	v_cvt_pk_bf16_f32 v49, v229, v231
	v_cvt_pk_bf16_f32 v50, v236, v237
	v_cvt_pk_bf16_f32 v51, v240, v241
	v_cvt_pk_bf16_f32 v52, v172, v177
	v_cvt_pk_bf16_f32 v53, v212, v213
	v_cvt_pk_bf16_f32 v54, v232, v233
	v_cvt_pk_bf16_f32 v55, v238, v239
	v_cvt_pk_bf16_f32 v56, v173, v192
	v_cvt_pk_bf16_f32 v57, v206, v207
	v_cvt_pk_bf16_f32 v58, v214, v215
	v_cvt_pk_bf16_f32 v59, v234, v235
	v_cvt_pk_bf16_f32 v60, v195, v193
	v_cvt_pk_bf16_f32 v61, v203, v201
	v_cvt_pk_bf16_f32 v62, v211, v209
	v_cvt_pk_bf16_f32 v63, v230, v228
	v_mov_b32_e32 v166, 0
	v_mov_b32_e32 v167, 1.0
	s_mov_b32 s19, 0
	s_mov_b32 s20, 3
	s_mov_b32 s67, 0xbfb8aa3b
	v_mul_f32_e32 v155, 0xbfb8aa3b, v155
	v_mul_f32_e32 v157, 0xbfb8aa3b, v157
	v_mul_f32_e32 v158, 0xbfb8aa3b, v158
	v_mul_f32_e32 v160, 0xbfb8aa3b, v160
	v_mul_f32_e32 v161, 0xbfb8aa3b, v161
	v_mul_f32_e32 v163, 0xbfb8aa3b, v163
	v_mul_f32_e32 v164, 0xbfb8aa3b, v164
	v_mul_f32_e32 v64, 0xbfb8aa3b, v64
	v_mul_f32_e32 v156, 0xc138aa3b, v156
	v_mul_f32_e32 v159, 0xc138aa3b, v159
	v_mul_f32_e32 v162, 0xc138aa3b, v162
	v_mul_f32_e32 v165, 0xc138aa3b, v165
.LBB0_466:
	s_and_b64 s[0:1], s[4:5], exec
	s_cselect_b32 s0, s19, s20
	s_lshl_b32 s21, s0, 4
	v_or_b32_e32 v66, s21, v93
	v_mad_u64_u32 v[66:67], s[0:1], v66, s58, v[92:93]
	ds_read_b128 v[70:73], v66
	ds_read_b128 v[66:69], v66 offset:64
	s_add_i32 s19, s19, 1
	s_add_i32 s20, s20, -1
	s_waitcnt lgkmcnt(1)
	v_mfma_f32_16x16x32_bf16 v[74:77], v[70:73], v[0:3], 0
	s_cmp_lg_u32 s19, 4
	s_waitcnt lgkmcnt(0)
	v_mfma_f32_16x16x32_bf16 v[74:77], v[66:69], v[16:19], v[74:77]
	v_mfma_f32_16x16x32_bf16 v[98:101], v[70:73], v[32:35], 0
	v_mfma_f32_16x16x32_bf16 v[168:171], v[66:69], v[48:51], v[98:101]
	s_nop 5
	v_fma_f32 v74, v74, s67, v64
	v_exp_f32_e32 v74, v74
	s_nop 0
	v_add_f32_e32 v74, 1.0, v74
	v_rcp_f32_e32 v74, v74
	v_fma_f32 v98, v168, s67, v155
	v_exp_f32_e32 v98, v98
	v_mul_f32_e32 v74, v156, v74
	v_add_f32_e32 v98, 1.0, v98
	v_exp_f32_e32 v74, v74
	ds_write_b32 v108, v74 offset:33792
	v_fma_f32 v74, -v74, v74, 1.0
	v_max_f32_e32 v74, 0, v74
	v_rcp_f32_e32 v98, v98
	v_or_b32_e32 v99, s21, v106
	v_mad_u64_u32 v[104:105], s[0:1], v99, s58, v[96:97]
	ds_read_u16 v99, v104
	s_waitcnt lgkmcnt(0)
	v_lshlrev_b32_e32 v99, 16, v99
	v_sqrt_f32_e32 v74, v74
	s_nop 0
	v_mul_f32_e32 v74, v98, v74
	v_mul_f32_e32 v74, v74, v99
	v_cvt_pk_bf16_f32 v74, v74, s0
	ds_write_b16 v136, v74 offset:38144
	v_fma_f32 v74, v75, s67, v64
	v_exp_f32_e32 v74, v74
	s_nop 0
	v_add_f32_e32 v74, 1.0, v74
	v_rcp_f32_e32 v74, v74
	v_fma_f32 v75, v169, s67, v155
	v_exp_f32_e32 v75, v75
	v_mul_f32_e32 v74, v156, v74
	v_add_f32_e32 v75, 1.0, v75
	v_exp_f32_e32 v74, v74
	ds_write_b32 v110, v74 offset:33792
	v_fma_f32 v74, -v74, v74, 1.0
	v_max_f32_e32 v74, 0, v74
	v_rcp_f32_e32 v75, v75
	v_or_b32_e32 v98, s21, v109
	v_mad_u64_u32 v[102:103], s[0:1], v98, s58, v[96:97]
	ds_read_u16 v98, v102
	s_waitcnt lgkmcnt(0)
	v_lshlrev_b32_e32 v98, 16, v98
	v_sqrt_f32_e32 v74, v74
	s_nop 0
	v_mul_f32_e32 v74, v75, v74
	v_mul_f32_e32 v74, v74, v98
	v_cvt_pk_bf16_f32 v74, v74, s0
	ds_write_b16 v137, v74 offset:38144
	v_fma_f32 v74, v76, s67, v64
	v_exp_f32_e32 v74, v74
	s_nop 0
	v_add_f32_e32 v74, 1.0, v74
	v_rcp_f32_e32 v74, v74
	v_fma_f32 v75, v170, s67, v155
	v_exp_f32_e32 v75, v75
	v_mul_f32_e32 v74, v156, v74
	v_add_f32_e32 v75, 1.0, v75
	v_exp_f32_e32 v74, v74
	ds_write_b32 v112, v74 offset:33792
	v_fma_f32 v74, -v74, v74, 1.0
	v_max_f32_e32 v74, 0, v74
	v_rcp_f32_e32 v75, v75
	v_or_b32_e32 v76, s21, v111
	v_mad_u64_u32 v[100:101], s[0:1], v76, s58, v[96:97]
	ds_read_u16 v76, v100
	s_waitcnt lgkmcnt(0)
; __device__ __forceinline__ bf16_t f2bf(float f) { return (bf16_t)(cvt_pk_bf16(f, 0.f) & 0xffffu); }
; __device__ __forceinline__ float bf2f(bf16_t b) { return __uint_as_float(((unsigned)b) << 16); }
; __device__ __forceinline__ float sigmoidf_(float x) { return 1.0f / (1.0f + __expf(-x)); }
; template <bool FINAL>
; __device__ __forceinline__ void lru_item(const Ctx& C, int l, int item) {
;     ...
; #pragma unroll
;             for (int dt = 0; dt < 4; ++dt) {
;                 f32x4 Da = {0.f, 0.f, 0.f, 0.f}, Dx = {0.f, 0.f, 0.f, 0.f};
;                 Da = __builtin_amdgcn_mfma_f32_16x16x32_bf16(xa0, Bw[0][dt][0], Da, 0, 0, 0); Da = __builtin_amdgcn_mfma_f32_16x16x32_bf16(xa1, Bw[0][dt][1], Da, 0, 0, 0);
;                 Dx = __builtin_amdgcn_mfma_f32_16x16x32_bf16(xa0, Bw[1][dt][0], Dx, 0, 0, 0); Dx = __builtin_amdgcn_mfma_f32_16x16x32_bf16(xa1, Bw[1][dt][1], Dx, 0, 0, 0);
; #pragma unroll
;                 for (int r = 0; r < 4; ++r) { const int tloc = 4 * quad + r, d = 16 * dt + fr;
;                     const float rg = sigmoidf_(Da[r] + bav[dt]), ig = sigmoidf_(Dx[r] + bxv[dt]), la = -8.0f * rg * spv[dt], a = __expf(la);
;                     const float x = bf2f(xc[(16 * tt + tloc) * XCP + n * 64 + d]);
;                     Al[tloc * 68 + d] = a; Ul[tloc * 68 + d] = f2bf(sqrtf(fmaxf(1.0f - a * a, 0.f)) * ig * x); }
	v_lshlrev_b32_e32 v76, 16, v76
	v_sqrt_f32_e32 v74, v74
	s_nop 0
	v_mul_f32_e32 v74, v75, v74
	v_mul_f32_e32 v74, v74, v76
	v_cvt_pk_bf16_f32 v74, v74, s0
	ds_write_b16 v138, v74 offset:38144
	v_fma_f32 v74, v77, s67, v64
	v_exp_f32_e32 v74, v74
	s_nop 0
	v_add_f32_e32 v74, 1.0, v74
	v_rcp_f32_e32 v74, v74
	v_fma_f32 v75, v171, s67, v155
	v_exp_f32_e32 v75, v75
	v_mul_f32_e32 v74, v156, v74
	v_add_f32_e32 v75, 1.0, v75
	v_exp_f32_e32 v74, v74
	v_mfma_f32_16x16x32_bf16 v[168:171], v[70:73], v[36:39], 0
	ds_write_b32 v114, v74 offset:33792
	v_fma_f32 v74, -v74, v74, 1.0
	v_max_f32_e32 v74, 0, v74
	v_rcp_f32_e32 v75, v75
	v_or_b32_e32 v76, s21, v113
	v_mad_u64_u32 v[98:99], s[0:1], v76, s58, v[96:97]
	ds_read_u16 v76, v98
	v_mfma_f32_16x16x32_bf16 v[168:171], v[66:69], v[52:55], v[168:171]
	s_waitcnt lgkmcnt(0)
	v_lshlrev_b32_e32 v76, 16, v76
	v_sqrt_f32_e32 v74, v74
	s_nop 0
	v_mul_f32_e32 v74, v75, v74
	v_mul_f32_e32 v74, v74, v76
	v_cvt_pk_bf16_f32 v74, v74, s0
	ds_write_b16 v139, v74 offset:38144
	v_mfma_f32_16x16x32_bf16 v[74:77], v[70:73], v[4:7], 0
	v_mfma_f32_16x16x32_bf16 v[74:77], v[66:69], v[20:23], v[74:77]
	s_nop 7
	v_fma_f32 v74, v74, s67, v157
	v_exp_f32_e32 v74, v74
	s_nop 0
	v_add_f32_e32 v74, 1.0, v74
	v_rcp_f32_e32 v74, v74
	v_fma_f32 v99, v168, s67, v158
	v_exp_f32_e32 v99, v99
	v_mul_f32_e32 v74, v159, v74
	v_add_f32_e32 v99, 1.0, v99
	v_exp_f32_e32 v74, v74
	ds_write_b32 v108, v74 offset:33856
	v_fma_f32 v74, -v74, v74, 1.0
	v_max_f32_e32 v74, 0, v74
	v_rcp_f32_e32 v99, v99
	ds_read_u16 v101, v104 offset:32
	s_waitcnt lgkmcnt(0)
	v_lshlrev_b32_e32 v101, 16, v101
	v_sqrt_f32_e32 v74, v74
	s_nop 0
	v_mul_f32_e32 v74, v99, v74
	v_mul_f32_e32 v74, v74, v101
	v_cvt_pk_bf16_f32 v74, v74, s0
	ds_write_b16 v115, v74 offset:38176
	v_fma_f32 v74, v75, s67, v157
	v_exp_f32_e32 v74, v74
	s_nop 0
	v_add_f32_e32 v74, 1.0, v74
	v_rcp_f32_e32 v74, v74
	v_fma_f32 v75, v169, s67, v158
	v_exp_f32_e32 v75, v75
	v_mul_f32_e32 v74, v159, v74
	v_add_f32_e32 v75, 1.0, v75
	v_exp_f32_e32 v74, v74
	ds_write_b32 v110, v74 offset:33856
	v_fma_f32 v74, -v74, v74, 1.0
	v_max_f32_e32 v74, 0, v74
	v_rcp_f32_e32 v75, v75
	ds_read_u16 v99, v102 offset:32
	s_waitcnt lgkmcnt(0)
	v_lshlrev_b32_e32 v99, 16, v99
	v_sqrt_f32_e32 v74, v74
	s_nop 0
	v_mul_f32_e32 v74, v75, v74
	v_mul_f32_e32 v74, v74, v99
	v_cvt_pk_bf16_f32 v74, v74, s0
	ds_write_b16 v116, v74 offset:38176
	v_fma_f32 v74, v76, s67, v157
	v_exp_f32_e32 v74, v74
	s_nop 0
	v_add_f32_e32 v74, 1.0, v74
	v_rcp_f32_e32 v74, v74
	v_fma_f32 v75, v170, s67, v158
	v_exp_f32_e32 v75, v75
	v_mul_f32_e32 v74, v159, v74
	v_add_f32_e32 v75, 1.0, v75
	v_exp_f32_e32 v74, v74
	ds_write_b32 v112, v74 offset:33856
	v_fma_f32 v74, -v74, v74, 1.0
	v_max_f32_e32 v74, 0, v74
	v_rcp_f32_e32 v75, v75
	ds_read_u16 v76, v100 offset:32
	s_waitcnt lgkmcnt(0)
	v_lshlrev_b32_e32 v76, 16, v76
	v_sqrt_f32_e32 v74, v74
	s_nop 0
	v_mul_f32_e32 v74, v75, v74
	v_mul_f32_e32 v74, v74, v76
	v_cvt_pk_bf16_f32 v74, v74, s0
	ds_write_b16 v117, v74 offset:38176
	v_fma_f32 v74, v77, s67, v157
	v_exp_f32_e32 v74, v74
	s_nop 0
	v_add_f32_e32 v74, 1.0, v74
	v_rcp_f32_e32 v74, v74
	v_fma_f32 v75, v171, s67, v158
	v_exp_f32_e32 v75, v75
	v_mul_f32_e32 v74, v159, v74
	v_add_f32_e32 v75, 1.0, v75
	v_exp_f32_e32 v74, v74
	v_mfma_f32_16x16x32_bf16 v[168:171], v[70:73], v[40:43], 0
	ds_write_b32 v114, v74 offset:33856
	v_fma_f32 v74, -v74, v74, 1.0
	v_max_f32_e32 v74, 0, v74
	v_rcp_f32_e32 v75, v75
	ds_read_u16 v76, v98 offset:32
	v_mfma_f32_16x16x32_bf16 v[168:171], v[66:69], v[56:59], v[168:171]
	s_waitcnt lgkmcnt(0)
	v_lshlrev_b32_e32 v76, 16, v76
	v_sqrt_f32_e32 v74, v74
	s_nop 0
	v_mul_f32_e32 v74, v75, v74
	v_mul_f32_e32 v74, v74, v76
	v_cvt_pk_bf16_f32 v74, v74, s0
	ds_write_b16 v118, v74 offset:38176
	v_mfma_f32_16x16x32_bf16 v[74:77], v[70:73], v[8:11], 0
	v_mfma_f32_16x16x32_bf16 v[74:77], v[66:69], v[24:27], v[74:77]
	s_nop 7
	v_fma_f32 v74, v74, s67, v160
	v_exp_f32_e32 v74, v74
	s_nop 0
	v_add_f32_e32 v74, 1.0, v74
	v_rcp_f32_e32 v74, v74
	v_fma_f32 v99, v168, s67, v161
	v_exp_f32_e32 v99, v99
	v_mul_f32_e32 v74, v162, v74
	v_add_f32_e32 v99, 1.0, v99
	v_exp_f32_e32 v74, v74
	ds_write_b32 v108, v74 offset:33920
	v_fma_f32 v74, -v74, v74, 1.0
	v_max_f32_e32 v74, 0, v74
	v_rcp_f32_e32 v99, v99
	ds_read_u16 v101, v104 offset:64
	s_waitcnt lgkmcnt(0)
	v_lshlrev_b32_e32 v101, 16, v101
	v_sqrt_f32_e32 v74, v74
	s_nop 0
	v_mul_f32_e32 v74, v99, v74
	v_mul_f32_e32 v74, v74, v101
	v_cvt_pk_bf16_f32 v74, v74, s0
	ds_write_b16 v115, v74 offset:38208
	v_fma_f32 v74, v75, s67, v160
	v_exp_f32_e32 v74, v74
	s_nop 0
	v_add_f32_e32 v74, 1.0, v74
	v_rcp_f32_e32 v74, v74
	v_fma_f32 v75, v169, s67, v161
	v_exp_f32_e32 v75, v75
	v_mul_f32_e32 v74, v162, v74
	v_add_f32_e32 v75, 1.0, v75
	v_exp_f32_e32 v74, v74
	ds_write_b32 v110, v74 offset:33920
	v_fma_f32 v74, -v74, v74, 1.0
	v_max_f32_e32 v74, 0, v74
	v_rcp_f32_e32 v75, v75
	ds_read_u16 v99, v102 offset:64
	s_waitcnt lgkmcnt(0)
	v_lshlrev_b32_e32 v99, 16, v99
	v_sqrt_f32_e32 v74, v74
	s_nop 0
	v_mul_f32_e32 v74, v75, v74
	v_mul_f32_e32 v74, v74, v99
	v_cvt_pk_bf16_f32 v74, v74, s0
	ds_write_b16 v116, v74 offset:38208
	v_fma_f32 v74, v76, s67, v160
	v_exp_f32_e32 v74, v74
	s_nop 0
	v_add_f32_e32 v74, 1.0, v74
	v_rcp_f32_e32 v74, v74
	v_fma_f32 v75, v170, s67, v161
	v_exp_f32_e32 v75, v75
	v_mul_f32_e32 v74, v162, v74
	v_add_f32_e32 v75, 1.0, v75
	v_exp_f32_e32 v74, v74
	ds_write_b32 v112, v74 offset:33920
	v_fma_f32 v74, -v74, v74, 1.0
	v_max_f32_e32 v74, 0, v74
	v_rcp_f32_e32 v75, v75
	ds_read_u16 v76, v100 offset:64
	s_waitcnt lgkmcnt(0)
; __device__ __forceinline__ bf16_t f2bf(float f) { return (bf16_t)(cvt_pk_bf16(f, 0.f) & 0xffffu); }
; __device__ __forceinline__ float bf2f(bf16_t b) { return __uint_as_float(((unsigned)b) << 16); }
; __device__ __forceinline__ float sigmoidf_(float x) { return 1.0f / (1.0f + __expf(-x)); }
; __device__ __forceinline__ void wave_lds_fence() { asm volatile("s_waitcnt lgkmcnt(0)" ::: "memory"); __builtin_amdgcn_wave_barrier(); }
; template <bool FINAL>
; __device__ __forceinline__ void lru_item(const Ctx& C, int l, int item) {
;     ...
; #pragma unroll
;             for (int dt = 0; dt < 4; ++dt) {
;                 f32x4 Da = {0.f, 0.f, 0.f, 0.f}, Dx = {0.f, 0.f, 0.f, 0.f};
;                 Da = __builtin_amdgcn_mfma_f32_16x16x32_bf16(xa0, Bw[0][dt][0], Da, 0, 0, 0); Da = __builtin_amdgcn_mfma_f32_16x16x32_bf16(xa1, Bw[0][dt][1], Da, 0, 0, 0);
;                 Dx = __builtin_amdgcn_mfma_f32_16x16x32_bf16(xa0, Bw[1][dt][0], Dx, 0, 0, 0); Dx = __builtin_amdgcn_mfma_f32_16x16x32_bf16(xa1, Bw[1][dt][1], Dx, 0, 0, 0);
; #pragma unroll
;                 for (int r = 0; r < 4; ++r) { const int tloc = 4 * quad + r, d = 16 * dt + fr;
;                     const float rg = sigmoidf_(Da[r] + bav[dt]), ig = sigmoidf_(Dx[r] + bxv[dt]), la = -8.0f * rg * spv[dt], a = __expf(la);
;                     const float x = bf2f(xc[(16 * tt + tloc) * XCP + n * 64 + d]);
;                     Al[tloc * 68 + d] = a; Ul[tloc * 68 + d] = f2bf(sqrtf(fmaxf(1.0f - a * a, 0.f)) * ig * x); }
;             }
;             wave_lds_fence();
; #pragma unroll
;             for (int j = 0; j < 16; ++j) { const int tloc = z ? 15 - j : j;
;                 const float a = Al[tloc * 68 + lane], u = bf2f(Ul[tloc * 68 + lane]);
;                 h = fmaf(a, h, u); Ap *= a;
;                 if (FINAL) Hz[(16 * tt + tloc) * 256 + n * 64 + lane] = f2bf(h); }
;             wave_lds_fence();
	v_lshlrev_b32_e32 v76, 16, v76
	v_sqrt_f32_e32 v74, v74
	s_nop 0
	v_mul_f32_e32 v74, v75, v74
	v_mul_f32_e32 v74, v74, v76
	v_cvt_pk_bf16_f32 v74, v74, s0
	ds_write_b16 v117, v74 offset:38208
	v_fma_f32 v74, v77, s67, v160
	v_exp_f32_e32 v74, v74
	s_nop 0
	v_add_f32_e32 v74, 1.0, v74
	v_rcp_f32_e32 v74, v74
	v_fma_f32 v75, v171, s67, v161
	v_exp_f32_e32 v75, v75
	v_mul_f32_e32 v74, v162, v74
	v_add_f32_e32 v75, 1.0, v75
	v_exp_f32_e32 v74, v74
	ds_write_b32 v114, v74 offset:33920
	v_fma_f32 v74, -v74, v74, 1.0
	v_max_f32_e32 v74, 0, v74
	v_rcp_f32_e32 v75, v75
	ds_read_u16 v76, v98 offset:64
	s_waitcnt lgkmcnt(0)
	v_lshlrev_b32_e32 v76, 16, v76
	v_sqrt_f32_e32 v74, v74
	s_nop 0
	v_mul_f32_e32 v74, v75, v74
	v_mul_f32_e32 v74, v74, v76
	v_cvt_pk_bf16_f32 v74, v74, s0
	ds_write_b16 v118, v74 offset:38208
	v_mfma_f32_16x16x32_bf16 v[74:77], v[70:73], v[12:15], 0
	v_mfma_f32_16x16x32_bf16 v[74:77], v[66:69], v[28:31], v[74:77]
	v_mfma_f32_16x16x32_bf16 v[70:73], v[70:73], v[44:47], 0
	v_mfma_f32_16x16x32_bf16 v[66:69], v[66:69], v[60:63], v[70:73]
	s_waitcnt vmcnt(1)
	s_nop 5
	v_fma_f32 v70, v74, s67, v163
	v_exp_f32_e32 v70, v70
	s_waitcnt vmcnt(0)
	v_fma_f32 v66, v66, s67, v164
	v_exp_f32_e32 v66, v66
	v_add_f32_e32 v70, 1.0, v70
	v_add_f32_e32 v66, 1.0, v66
	v_fma_f32 v67, v67, s67, v164
	v_rcp_f32_e32 v70, v70
	s_nop 0
	v_mul_f32_e32 v70, v165, v70
	v_exp_f32_e32 v70, v70
	ds_write_b32 v108, v70 offset:33984
	v_fma_f32 v70, -v70, v70, 1.0
	v_max_f32_e32 v70, 0, v70
	v_rcp_f32_e32 v66, v66
	ds_read_u16 v71, v104 offset:96
	v_exp_f32_e32 v67, v67
	s_waitcnt lgkmcnt(0)
	v_lshlrev_b32_e32 v71, 16, v71
	v_add_f32_e32 v67, 1.0, v67
	v_sqrt_f32_e32 v70, v70
	s_nop 0
	v_mul_f32_e32 v66, v66, v70
	v_mul_f32_e32 v66, v66, v71
	v_cvt_pk_bf16_f32 v66, v66, s0
	ds_write_b16 v115, v66 offset:38240
	v_fma_f32 v66, v75, s67, v163
	v_exp_f32_e32 v66, v66
	s_nop 0
	v_add_f32_e32 v66, 1.0, v66
	v_rcp_f32_e32 v66, v66
	s_nop 0
	v_mul_f32_e32 v66, v165, v66
	v_exp_f32_e32 v66, v66
	ds_write_b32 v110, v66 offset:33984
	v_fma_f32 v66, -v66, v66, 1.0
	v_max_f32_e32 v66, 0, v66
	v_rcp_f32_e32 v67, v67
	ds_read_u16 v70, v102 offset:96
	s_waitcnt lgkmcnt(0)
	v_lshlrev_b32_e32 v70, 16, v70
	v_sqrt_f32_e32 v66, v66
	s_nop 0
	v_mul_f32_e32 v66, v67, v66
	v_mul_f32_e32 v66, v66, v70
	v_cvt_pk_bf16_f32 v66, v66, s0
	ds_write_b16 v116, v66 offset:38240
	v_fma_f32 v66, v76, s67, v163
	v_exp_f32_e32 v66, v66
	s_nop 0
	v_add_f32_e32 v66, 1.0, v66
	v_rcp_f32_e32 v66, v66
	v_fma_f32 v67, v68, s67, v164
	v_exp_f32_e32 v67, v67
	v_mul_f32_e32 v66, v165, v66
	v_add_f32_e32 v67, 1.0, v67
	v_exp_f32_e32 v66, v66
	ds_write_b32 v112, v66 offset:33984
	v_fma_f32 v66, -v66, v66, 1.0
	v_max_f32_e32 v66, 0, v66
	v_rcp_f32_e32 v67, v67
	ds_read_u16 v68, v100 offset:96
	s_waitcnt lgkmcnt(0)
	v_lshlrev_b32_e32 v68, 16, v68
	v_sqrt_f32_e32 v66, v66
	s_nop 0
	v_mul_f32_e32 v66, v67, v66
	v_mul_f32_e32 v66, v66, v68
	v_cvt_pk_bf16_f32 v66, v66, s0
	ds_write_b16 v117, v66 offset:38240
	v_fma_f32 v66, v77, s67, v163
	v_exp_f32_e32 v66, v66
	s_nop 0
	v_add_f32_e32 v66, 1.0, v66
	v_rcp_f32_e32 v66, v66
	v_fma_f32 v67, v69, s67, v164
	v_exp_f32_e32 v67, v67
	v_mul_f32_e32 v66, v165, v66
	v_add_f32_e32 v67, 1.0, v67
	v_exp_f32_e32 v66, v66
	ds_write_b32 v114, v66 offset:33984
	v_fma_f32 v66, -v66, v66, 1.0
	v_max_f32_e32 v66, 0, v66
	v_rcp_f32_e32 v67, v67
	ds_read_u16 v68, v98 offset:96
	s_waitcnt lgkmcnt(0)
	v_lshlrev_b32_e32 v68, 16, v68
	v_sqrt_f32_e32 v66, v66
	s_nop 0
	v_mul_f32_e32 v66, v67, v66
	v_mul_f32_e32 v66, v66, v68
	v_cvt_pk_bf16_f32 v66, v66, s0
	ds_write_b16 v118, v66 offset:38240
	s_waitcnt lgkmcnt(0)
	ds_read_b32 v66, v107 offset:33792
	ds_read_u16 v67, v119 offset:38144
	ds_read_b32 v68, v120 offset:33792
	ds_read_u16 v69, v140 offset:38144
	s_waitcnt lgkmcnt(2)
	v_lshlrev_b32_e32 v67, 16, v67
	v_fmac_f32_e32 v67, v66, v166
	v_mul_f32_e32 v66, v167, v66
	s_waitcnt lgkmcnt(0)
	v_lshlrev_b32_e32 v69, 16, v69
	v_fmac_f32_e32 v69, v68, v67
	v_mul_f32_e32 v66, v66, v68
	ds_read_b32 v67, v121 offset:33792
	ds_read_u16 v68, v141 offset:38144
	s_waitcnt lgkmcnt(1)
	v_mul_f32_e32 v66, v66, v67
	s_waitcnt lgkmcnt(0)
	v_lshlrev_b32_e32 v68, 16, v68
	v_fmac_f32_e32 v68, v67, v69
	ds_read_b32 v67, v122 offset:33792
	ds_read_u16 v69, v142 offset:38144
	s_waitcnt lgkmcnt(1)
	v_mul_f32_e32 v66, v66, v67
	s_waitcnt lgkmcnt(0)
	v_lshlrev_b32_e32 v69, 16, v69
	v_fmac_f32_e32 v69, v67, v68
	ds_read_b32 v67, v123 offset:33792
	ds_read_u16 v68, v143 offset:38144
	s_waitcnt lgkmcnt(1)
	v_mul_f32_e32 v66, v66, v67
	s_waitcnt lgkmcnt(0)
	v_lshlrev_b32_e32 v68, 16, v68
	v_fmac_f32_e32 v68, v67, v69
	ds_read_b32 v67, v124 offset:33792
	ds_read_u16 v69, v144 offset:38144
	s_waitcnt lgkmcnt(1)
	v_mul_f32_e32 v66, v66, v67
	s_waitcnt lgkmcnt(0)
	v_lshlrev_b32_e32 v69, 16, v69
	v_fmac_f32_e32 v69, v67, v68
	ds_read_b32 v67, v125 offset:33792
	ds_read_u16 v68, v145 offset:38144
	s_waitcnt lgkmcnt(1)
	v_mul_f32_e32 v66, v66, v67
	s_waitcnt lgkmcnt(0)
	v_lshlrev_b32_e32 v68, 16, v68
	v_fmac_f32_e32 v68, v67, v69
	ds_read_b32 v67, v126 offset:33792
	ds_read_u16 v69, v146 offset:38144
	s_waitcnt lgkmcnt(1)
	v_mul_f32_e32 v66, v66, v67
	s_waitcnt lgkmcnt(0)
	v_lshlrev_b32_e32 v69, 16, v69
	v_fmac_f32_e32 v69, v67, v68
	ds_read_b32 v67, v127 offset:33792
	ds_read_u16 v68, v147 offset:38144
	s_waitcnt lgkmcnt(1)
	v_mul_f32_e32 v66, v66, v67
	s_waitcnt lgkmcnt(0)
	v_lshlrev_b32_e32 v68, 16, v68
	v_fmac_f32_e32 v68, v67, v69
	ds_read_b32 v67, v128 offset:33792
	ds_read_u16 v69, v148 offset:38144
	s_waitcnt lgkmcnt(1)
	v_mul_f32_e32 v66, v66, v67
	s_waitcnt lgkmcnt(0)
	v_lshlrev_b32_e32 v69, 16, v69
	v_fmac_f32_e32 v69, v67, v68
	ds_read_b32 v67, v129 offset:33792
	ds_read_u16 v68, v149 offset:38144
	s_waitcnt lgkmcnt(1)
	v_mul_f32_e32 v66, v66, v67
	s_waitcnt lgkmcnt(0)
	v_lshlrev_b32_e32 v68, 16, v68
	v_fmac_f32_e32 v68, v67, v69
	ds_read_b32 v67, v130 offset:33792
	ds_read_u16 v69, v150 offset:38144
	s_waitcnt lgkmcnt(1)
	v_mul_f32_e32 v66, v66, v67
	s_waitcnt lgkmcnt(0)
	v_lshlrev_b32_e32 v69, 16, v69
	v_fmac_f32_e32 v69, v67, v68
	ds_read_b32 v67, v131 offset:33792
	ds_read_u16 v68, v151 offset:38144
	s_waitcnt lgkmcnt(1)
	v_mul_f32_e32 v66, v66, v67
	s_waitcnt lgkmcnt(0)
	v_lshlrev_b32_e32 v68, 16, v68
	v_fmac_f32_e32 v68, v67, v69
	ds_read_b32 v67, v132 offset:33792
	ds_read_u16 v69, v152 offset:38144
	s_waitcnt lgkmcnt(1)
	v_mul_f32_e32 v66, v66, v67
	s_waitcnt lgkmcnt(0)
	v_lshlrev_b32_e32 v69, 16, v69
	v_fmac_f32_e32 v69, v67, v68
	ds_read_b32 v67, v133 offset:33792
	ds_read_u16 v68, v153 offset:38144
	s_waitcnt lgkmcnt(1)
	v_mul_f32_e32 v66, v66, v67
	s_waitcnt lgkmcnt(0)
	v_lshlrev_b32_e32 v68, 16, v68
	v_fmac_f32_e32 v68, v67, v69
	ds_read_b32 v67, v134 offset:33792
	ds_read_u16 v69, v154 offset:38144
	s_waitcnt lgkmcnt(0)
	s_waitcnt lgkmcnt(1)
	v_mul_f32_e32 v167, v66, v67
	s_waitcnt lgkmcnt(0)
	v_lshlrev_b32_e32 v166, 16, v69
	v_fmac_f32_e32 v166, v67, v68
	s_cbranch_scc1 .LBB0_466
; __device__ __forceinline__ bf16_t f2bf(float f) { return (bf16_t)(cvt_pk_bf16(f, 0.f) & 0xffffu); }
; __device__ __forceinline__ float bf2f(bf16_t b) { return __uint_as_float(((unsigned)b) << 16); }
; __device__ __forceinline__ float geluf_(float x) { const float y = 0.7978845608028654f * (x + 0.044715f * x * x * x); const float t = 1.0f - 2.0f / (1.0f + __expf(2.0f * y)); return 0.5f * x * (1.0f + t); }
;     __device__ __forceinline__ bf16_t* bfp(size_t off) const { return (bf16_t*)(ws + off); }
;     __device__ __forceinline__ float* fp(size_t off) const { return (float*)(ws + off); }
; template <bool FINAL>
; __device__ __forceinline__ void lru_item(const Ctx& C, int l, int item) {
;     ...
;         if (!FINAL) { C.fp(OFF_CARA)[cidx] = Ap; C.fp(OFF_CARH)[cidx] = h; }
;     }
;     if (FINAL) {
;         __syncthreads();
;         int ch = tid & 255; asm volatile("" : "+v"(ch)); const int zz = tid >> 8;
;         const bf16_t* gp = pb + (size_t)(b * SEQ + c * 64) * 512 + 256 + ch; bf16_t* yb = C.bfp(OFF_YB) + (size_t)(b * SEQ + c * 64) * 256 + ch;
; #pragma unroll 1
;         for (int k8 = 0; k8 < 4; ++k8) { bf16_t gv_[8];
; #pragma unroll
;             for (int k = 0; k < 8; ++k) gv_[k] = gp[(size_t)(zz * 32 + k8 * 8 + k) * 512];
; #pragma unroll
;             for (int k = 0; k < 8; ++k) { const int tl = zz * 32 + k8 * 8 + k; const float hs = bf2f(H0[tl * 256 + ch]) + bf2f(H1[tl * 256 + ch]);
;                 yb[(size_t)tl * 256] = f2bf(hs * geluf_(bf2f(gv_[k]))); } }
;     }
;     __syncthreads();
	s_and_b32 s0, s17, 0xffffffc0
	s_add_i32 s0, s0, s14
	s_or_b32 s0, s0, s18
	s_ashr_i32 s1, s0, 31
	s_lshl_b64 s[0:1], s[0:1], 10
	v_lshl_or_b32 v0, v94, 2, s0
	v_readlane_b32 s0, v254, 27
	v_mov_b32_e32 v1, s1
	s_add_i32 s17, s17, s26
	s_add_i32 s16, s16, s26
	s_add_i32 s15, s15, s0
	v_lshl_add_u64 v[2:3], s[6:7], 0, v[0:1]
	v_lshl_add_u64 v[0:1], s[8:9], 0, v[0:1]
	s_cmpk_gt_i32 s17, 0x1ff
	global_store_dword v[2:3], v167, off
	global_store_dword v[0:1], v166, off
	s_barrier
	s_cbranch_scc0 .LBB0_435

; template <bool FINAL>
; __device__ __forceinline__ void lru_item(const Ctx& C, int l, int item) {
;     ...
;                 for (int dt = 0; dt < 4; ++dt) {
;                     union { bf16x8 v; unsigned u[4]; } t_; t_.u[0] = cvt_pk_bf16(f[dt][0], f[dt][1]); t_.u[1] = cvt_pk_bf16(f[dt][2], f[dt][3]); t_.u[2] = cvt_pk_bf16(f[dt][4], f[dt][5]); t_.u[3] = cvt_pk_bf16(f[dt][6], f[dt][7]); Bw[ty][dt][ks] = t_.v; }
;                 asm volatile("" ::: "memory");
;             }
;     {
;         int ch = tid & 255; asm volatile("" : "+v"(ch)); const int hf = tid >> 8;
;         const float w0 = C.P->in[5][(l * 4 + 0) * 256 + ch], w1 = C.P->in[5][(l * 4 + 1) * 256 + ch], w2 = C.P->in[5][(l * 4 + 2) * 256 + ch], w3 = C.P->in[5][(l * 4 + 3) * 256 + ch], cb = C.P->in[6][l * 256 + ch];
;         const int tl0 = hf * 32, t0 = c * 64 + tl0;
;         const bf16_t* colp = pb + (size_t)(b * SEQ) * 512 + ch;
;         float xm2 = (t0 - 2 >= 0) ? bf2f(colp[(size_t)(t0 - 2) * 512]) : 0.f, xm1 = (t0 - 1 >= 0) ? bf2f(colp[(size_t)(t0 - 1) * 512]) : 0.f, x0 = bf2f(colp[(size_t)t0 * 512]);
; #pragma unroll 1
;         for (int k8 = 0; k8 < 4; ++k8) { float xn[8];
; #pragma unroll
;             for (int k = 0; k < 8; ++k) { const int t = t0 + k8 * 8 + k + 1; xn[k] = (t < SEQ) ? bf2f(colp[(size_t)t * 512]) : 0.f; }
; #pragma unroll
;             for (int k = 0; k < 8; ++k) { xc[(tl0 + k8 * 8 + k) * XCP + ch] = f2bf(cb + w0 * xm2 + w1 * xm1 + w2 * x0 + w3 * xn[k]); xm2 = xm1; xm1 = x0; x0 = xn[k]; } }
;     }
;     __syncthreads();
;     {
;         float bav[4], bxv[4], spv[4];
; #pragma unroll
;         for (int dt = 0; dt < 4; ++dt) { const int chd = n * 64 + 16 * dt + fr; bav[dt] = C.P->in[8][(l * 2 + z) * 256 + chd]; bxv[dt] = C.P->in[10][(l * 2 + z) * 256 + chd];
;             const float lam = C.P->in[11][(l * 2 + z) * 256 + chd]; spv[dt] = (-lam > 15.f) ? -lam : log1pf(__expf(-lam)); }
;         const size_t cidx = (size_t)((z * 8 + b) * 64 + c) * 256 + n * 64 + lane;
;         float h = FINAL ? C.fp(OFF_CARH)[cidx] : 0.f, Ap = 1.f;
;         bf16_t* Hz = z ? H1 : H0;
; #pragma unroll 1
;         for (int s4 = 0; s4 < 4; ++s4) { const int tt = z ? 3 - s4 : s4;
;             const bf16_t* xrow = xc + (16 * tt + fr) * XCP + n * 64 + 8 * quad;
;             const bf16x8 xa0 = *(const bf16x8*)xrow, xa1 = *(const bf16x8*)(xrow + 32);
; #pragma unroll
.LBB0_680:
	s_or_b64 exec, exec, s[0:1]
	s_and_b32 s0, s48, 0xffffffc0
	s_add_i32 s0, s0, s12
	s_or_b32 s0, s0, s51
	s_ashr_i32 s1, s0, 31
	s_lshl_b64 s[0:1], s[0:1], 10
	v_lshl_add_u64 v[0:1], v[94:95], 0, s[0:1]
	global_load_dword v173, v[0:1], off
	v_cvt_pk_bf16_f32 v0, v6, v7
	v_cvt_pk_bf16_f32 v1, v20, v21
	v_cvt_pk_bf16_f32 v2, v28, v29
	v_cvt_pk_bf16_f32 v3, v37, v39
	v_cvt_pk_bf16_f32 v4, v8, v9
	v_cvt_pk_bf16_f32 v5, v18, v19
	v_cvt_pk_bf16_f32 v6, v26, v27
	v_cvt_pk_bf16_f32 v7, v34, v35
	v_cvt_pk_bf16_f32 v8, v10, v11
	v_cvt_pk_bf16_f32 v9, v15, v17
	v_cvt_pk_bf16_f32 v10, v23, v25
	v_cvt_pk_bf16_f32 v11, v31, v33
	v_cvt_pk_bf16_f32 v12, v13, v12
	v_cvt_pk_bf16_f32 v13, v16, v14
	v_cvt_pk_bf16_f32 v14, v24, v22
	v_cvt_pk_bf16_f32 v15, v32, v30
	v_cvt_pk_bf16_f32 v16, v36, v38
	v_cvt_pk_bf16_f32 v17, v52, v53
	v_cvt_pk_bf16_f32 v18, v60, v61
	v_cvt_pk_bf16_f32 v19, v71, v73
	v_cvt_pk_bf16_f32 v20, v40, v41
	v_cvt_pk_bf16_f32 v21, v50, v51
	v_cvt_pk_bf16_f32 v22, v58, v59
	v_cvt_pk_bf16_f32 v23, v68, v69
	v_cvt_pk_bf16_f32 v24, v42, v43
	v_cvt_pk_bf16_f32 v25, v47, v49
	v_cvt_pk_bf16_f32 v26, v55, v57
	v_cvt_pk_bf16_f32 v27, v63, v67
	v_cvt_pk_bf16_f32 v28, v45, v44
	v_cvt_pk_bf16_f32 v29, v48, v46
	v_cvt_pk_bf16_f32 v30, v56, v54
	v_cvt_pk_bf16_f32 v31, v66, v62
	v_cvt_pk_bf16_f32 v32, v70, v72
	v_cvt_pk_bf16_f32 v33, v174, v175
	v_cvt_pk_bf16_f32 v34, v196, v197
	v_cvt_pk_bf16_f32 v35, v205, v207
	v_cvt_pk_bf16_f32 v36, v74, v75
	v_cvt_pk_bf16_f32 v37, v110, v111
	v_cvt_pk_bf16_f32 v38, v194, v195
	v_cvt_pk_bf16_f32 v39, v202, v203
	v_cvt_pk_bf16_f32 v40, v76, v77
	v_cvt_pk_bf16_f32 v41, v107, v109
	v_cvt_pk_bf16_f32 v42, v177, v193
	v_cvt_pk_bf16_f32 v43, v199, v201
	v_cvt_pk_bf16_f32 v44, v105, v104
	v_cvt_pk_bf16_f32 v45, v108, v106
	v_cvt_pk_bf16_f32 v46, v192, v176
	v_cvt_pk_bf16_f32 v47, v200, v198
	v_cvt_pk_bf16_f32 v48, v204, v206
	v_cvt_pk_bf16_f32 v49, v232, v233
	v_cvt_pk_bf16_f32 v50, v240, v241
	v_cvt_pk_bf16_f32 v51, v248, v249
	v_cvt_pk_bf16_f32 v52, v208, v209
	v_cvt_pk_bf16_f32 v53, v230, v231
	v_cvt_pk_bf16_f32 v54, v238, v239
	v_cvt_pk_bf16_f32 v55, v246, v247
	v_cvt_pk_bf16_f32 v56, v210, v211
	v_cvt_pk_bf16_f32 v57, v215, v229
	v_cvt_pk_bf16_f32 v58, v235, v237
	v_cvt_pk_bf16_f32 v59, v243, v245
	v_cvt_pk_bf16_f32 v60, v213, v212
	v_cvt_pk_bf16_f32 v61, v228, v214
	v_cvt_pk_bf16_f32 v62, v236, v234
	v_cvt_pk_bf16_f32 v63, v244, v242
	s_mov_b32 s9, 0
	s_mov_b32 s51, 3
	s_mov_b32 s67, 0xbfb8aa3b
	v_mul_f32_e32 v162, 0xbfb8aa3b, v162
	v_mul_f32_e32 v164, 0xbfb8aa3b, v164
	v_mul_f32_e32 v165, 0xbfb8aa3b, v165
	v_mul_f32_e32 v167, 0xbfb8aa3b, v167
	v_mul_f32_e32 v168, 0xbfb8aa3b, v168
	v_mul_f32_e32 v170, 0xbfb8aa3b, v170
	v_mul_f32_e32 v171, 0xbfb8aa3b, v171
	v_mul_f32_e32 v64, 0xbfb8aa3b, v64
	v_mul_f32_e32 v163, 0xc138aa3b, v163
	v_mul_f32_e32 v166, 0xc138aa3b, v166
	v_mul_f32_e32 v169, 0xc138aa3b, v169
	v_mul_f32_e32 v172, 0xc138aa3b, v172
.LBB0_681:
	s_and_b64 s[0:1], s[4:5], exec
	s_cselect_b32 s0, s9, s51
	s_lshl_b32 s52, s0, 4
	v_or_b32_e32 v66, s52, v97
	v_mad_u64_u32 v[66:67], s[0:1], v66, s58, v[96:97]
	ds_read_b128 v[70:73], v66
	ds_read_b128 v[66:69], v66 offset:64
	s_add_i32 s9, s9, 1
	s_add_i32 s51, s51, -1
	s_waitcnt lgkmcnt(1)
	v_mfma_f32_16x16x32_bf16 v[74:77], v[70:73], v[0:3], 0
	s_waitcnt lgkmcnt(0)
	v_mfma_f32_16x16x32_bf16 v[74:77], v[66:69], v[16:19], v[74:77]
	v_mfma_f32_16x16x32_bf16 v[104:107], v[70:73], v[32:35], 0
	v_mfma_f32_16x16x32_bf16 v[174:177], v[66:69], v[48:51], v[104:107]
	s_nop 5
	v_fma_f32 v74, v74, s67, v64
	v_exp_f32_e32 v74, v74
	s_nop 0
	v_add_f32_e32 v74, 1.0, v74
	v_rcp_f32_e32 v74, v74
	v_fma_f32 v104, v174, s67, v162
	v_exp_f32_e32 v104, v104
	v_mul_f32_e32 v74, v163, v74
	v_add_f32_e32 v104, 1.0, v104
	v_exp_f32_e32 v74, v74
	ds_write_b32 v114, v74 offset:33792
	v_fma_f32 v74, -v74, v74, 1.0
	v_max_f32_e32 v74, 0, v74
	v_rcp_f32_e32 v104, v104
	v_or_b32_e32 v105, s52, v112
	v_mad_u64_u32 v[110:111], s[0:1], v105, s58, v[98:99]
	ds_read_u16 v105, v110
	s_waitcnt lgkmcnt(0)
	v_lshlrev_b32_e32 v105, 16, v105
	v_sqrt_f32_e32 v74, v74
	s_nop 0
	v_mul_f32_e32 v74, v104, v74
	v_mul_f32_e32 v74, v74, v105
	v_cvt_pk_bf16_f32 v74, v74, s0
	ds_write_b16 v87, v74 offset:38144
	v_fma_f32 v74, v75, s67, v64
	v_exp_f32_e32 v74, v74
	s_nop 0
	v_add_f32_e32 v74, 1.0, v74
	v_rcp_f32_e32 v74, v74
	v_fma_f32 v75, v175, s67, v162
	v_exp_f32_e32 v75, v75
	v_mul_f32_e32 v74, v163, v74
	v_add_f32_e32 v75, 1.0, v75
	v_exp_f32_e32 v74, v74
	ds_write_b32 v116, v74 offset:33792
	v_fma_f32 v74, -v74, v74, 1.0
	v_max_f32_e32 v74, 0, v74
	v_rcp_f32_e32 v75, v75
	v_or_b32_e32 v104, s52, v115
	v_mad_u64_u32 v[108:109], s[0:1], v104, s58, v[98:99]
	ds_read_u16 v104, v108
	s_waitcnt lgkmcnt(0)
	v_lshlrev_b32_e32 v104, 16, v104
	v_sqrt_f32_e32 v74, v74
	s_nop 0
	v_mul_f32_e32 v74, v75, v74
	v_mul_f32_e32 v74, v74, v104
	v_cvt_pk_bf16_f32 v74, v74, s0
	ds_write_b16 v144, v74 offset:38144
	v_fma_f32 v74, v76, s67, v64
	v_exp_f32_e32 v74, v74
	s_nop 0
	v_add_f32_e32 v74, 1.0, v74
	v_rcp_f32_e32 v74, v74
	v_fma_f32 v75, v176, s67, v162
	v_exp_f32_e32 v75, v75
	v_mul_f32_e32 v74, v163, v74
	v_add_f32_e32 v75, 1.0, v75
	v_exp_f32_e32 v74, v74
	ds_write_b32 v118, v74 offset:33792
	v_fma_f32 v74, -v74, v74, 1.0
	v_max_f32_e32 v74, 0, v74
	v_rcp_f32_e32 v75, v75
	v_or_b32_e32 v76, s52, v117
	v_mad_u64_u32 v[106:107], s[0:1], v76, s58, v[98:99]
	ds_read_u16 v76, v106
	s_waitcnt lgkmcnt(0)
; __device__ __forceinline__ bf16_t f2bf(float f) { return (bf16_t)(cvt_pk_bf16(f, 0.f) & 0xffffu); }
; __device__ __forceinline__ float bf2f(bf16_t b) { return __uint_as_float(((unsigned)b) << 16); }
; __device__ __forceinline__ float sigmoidf_(float x) { return 1.0f / (1.0f + __expf(-x)); }
; template <bool FINAL>
; __device__ __forceinline__ void lru_item(const Ctx& C, int l, int item) {
;     ...
; #pragma unroll
;             for (int dt = 0; dt < 4; ++dt) {
;                 f32x4 Da = {0.f, 0.f, 0.f, 0.f}, Dx = {0.f, 0.f, 0.f, 0.f};
;                 Da = __builtin_amdgcn_mfma_f32_16x16x32_bf16(xa0, Bw[0][dt][0], Da, 0, 0, 0); Da = __builtin_amdgcn_mfma_f32_16x16x32_bf16(xa1, Bw[0][dt][1], Da, 0, 0, 0);
;                 Dx = __builtin_amdgcn_mfma_f32_16x16x32_bf16(xa0, Bw[1][dt][0], Dx, 0, 0, 0); Dx = __builtin_amdgcn_mfma_f32_16x16x32_bf16(xa1, Bw[1][dt][1], Dx, 0, 0, 0);
; #pragma unroll
;                 for (int r = 0; r < 4; ++r) { const int tloc = 4 * quad + r, d = 16 * dt + fr;
;                     const float rg = sigmoidf_(Da[r] + bav[dt]), ig = sigmoidf_(Dx[r] + bxv[dt]), la = -8.0f * rg * spv[dt], a = __expf(la);
;                     const float x = bf2f(xc[(16 * tt + tloc) * XCP + n * 64 + d]);
;                     Al[tloc * 68 + d] = a; Ul[tloc * 68 + d] = f2bf(sqrtf(fmaxf(1.0f - a * a, 0.f)) * ig * x); }
	v_lshlrev_b32_e32 v76, 16, v76
	v_sqrt_f32_e32 v74, v74
	s_nop 0
	v_mul_f32_e32 v74, v75, v74
	v_mul_f32_e32 v74, v74, v76
	v_cvt_pk_bf16_f32 v74, v74, s0
	ds_write_b16 v145, v74 offset:38144
	v_fma_f32 v74, v77, s67, v64
	v_exp_f32_e32 v74, v74
	s_nop 0
	v_add_f32_e32 v74, 1.0, v74
	v_rcp_f32_e32 v74, v74
	v_fma_f32 v75, v177, s67, v162
	v_exp_f32_e32 v75, v75
	v_mul_f32_e32 v74, v163, v74
	v_add_f32_e32 v75, 1.0, v75
	v_exp_f32_e32 v74, v74
	v_mfma_f32_16x16x32_bf16 v[174:177], v[70:73], v[36:39], 0
	ds_write_b32 v120, v74 offset:33792
	v_fma_f32 v74, -v74, v74, 1.0
	v_max_f32_e32 v74, 0, v74
	v_rcp_f32_e32 v75, v75
	v_or_b32_e32 v76, s52, v119
	v_mad_u64_u32 v[104:105], s[0:1], v76, s58, v[98:99]
	ds_read_u16 v76, v104
	v_mfma_f32_16x16x32_bf16 v[174:177], v[66:69], v[52:55], v[174:177]
	s_waitcnt lgkmcnt(0)
	v_lshlrev_b32_e32 v76, 16, v76
	v_sqrt_f32_e32 v74, v74
	s_nop 0
	v_mul_f32_e32 v74, v75, v74
	v_mul_f32_e32 v74, v74, v76
	v_cvt_pk_bf16_f32 v74, v74, s0
	ds_write_b16 v146, v74 offset:38144
	v_mfma_f32_16x16x32_bf16 v[74:77], v[70:73], v[4:7], 0
	v_mfma_f32_16x16x32_bf16 v[74:77], v[66:69], v[20:23], v[74:77]
	s_nop 7
	v_fma_f32 v74, v74, s67, v164
	v_exp_f32_e32 v74, v74
	s_nop 0
	v_add_f32_e32 v74, 1.0, v74
	v_rcp_f32_e32 v74, v74
	v_fma_f32 v105, v174, s67, v165
	v_exp_f32_e32 v105, v105
	v_mul_f32_e32 v74, v166, v74
	v_add_f32_e32 v105, 1.0, v105
	v_exp_f32_e32 v74, v74
	ds_write_b32 v114, v74 offset:33856
	v_fma_f32 v74, -v74, v74, 1.0
	v_max_f32_e32 v74, 0, v74
	v_rcp_f32_e32 v105, v105
	ds_read_u16 v107, v110 offset:32
	s_waitcnt lgkmcnt(0)
	v_lshlrev_b32_e32 v107, 16, v107
	v_sqrt_f32_e32 v74, v74
	s_nop 0
	v_mul_f32_e32 v74, v105, v74
	v_mul_f32_e32 v74, v74, v107
	v_cvt_pk_bf16_f32 v74, v74, s0
	ds_write_b16 v121, v74 offset:38176
	v_fma_f32 v74, v75, s67, v164
	v_exp_f32_e32 v74, v74
	s_nop 0
	v_add_f32_e32 v74, 1.0, v74
	v_rcp_f32_e32 v74, v74
	v_fma_f32 v75, v175, s67, v165
	v_exp_f32_e32 v75, v75
	v_mul_f32_e32 v74, v166, v74
	v_add_f32_e32 v75, 1.0, v75
	v_exp_f32_e32 v74, v74
	ds_write_b32 v116, v74 offset:33856
	v_fma_f32 v74, -v74, v74, 1.0
	v_max_f32_e32 v74, 0, v74
	v_rcp_f32_e32 v75, v75
	ds_read_u16 v105, v108 offset:32
	s_waitcnt lgkmcnt(0)
	v_lshlrev_b32_e32 v105, 16, v105
	v_sqrt_f32_e32 v74, v74
	s_nop 0
	v_mul_f32_e32 v74, v75, v74
	v_mul_f32_e32 v74, v74, v105
	v_cvt_pk_bf16_f32 v74, v74, s0
	ds_write_b16 v122, v74 offset:38176
	v_fma_f32 v74, v76, s67, v164
	v_exp_f32_e32 v74, v74
	s_nop 0
	v_add_f32_e32 v74, 1.0, v74
	v_rcp_f32_e32 v74, v74
	v_fma_f32 v75, v176, s67, v165
	v_exp_f32_e32 v75, v75
	v_mul_f32_e32 v74, v166, v74
	v_add_f32_e32 v75, 1.0, v75
	v_exp_f32_e32 v74, v74
	ds_write_b32 v118, v74 offset:33856
	v_fma_f32 v74, -v74, v74, 1.0
	v_max_f32_e32 v74, 0, v74
	v_rcp_f32_e32 v75, v75
	ds_read_u16 v76, v106 offset:32
	s_waitcnt lgkmcnt(0)
	v_lshlrev_b32_e32 v76, 16, v76
	v_sqrt_f32_e32 v74, v74
	s_nop 0
	v_mul_f32_e32 v74, v75, v74
	v_mul_f32_e32 v74, v74, v76
	v_cvt_pk_bf16_f32 v74, v74, s0
	ds_write_b16 v123, v74 offset:38176
	v_fma_f32 v74, v77, s67, v164
	v_exp_f32_e32 v74, v74
	s_nop 0
	v_add_f32_e32 v74, 1.0, v74
	v_rcp_f32_e32 v74, v74
	v_fma_f32 v75, v177, s67, v165
	v_exp_f32_e32 v75, v75
	v_mul_f32_e32 v74, v166, v74
	v_add_f32_e32 v75, 1.0, v75
	v_exp_f32_e32 v74, v74
	v_mfma_f32_16x16x32_bf16 v[174:177], v[70:73], v[40:43], 0
	ds_write_b32 v120, v74 offset:33856
	v_fma_f32 v74, -v74, v74, 1.0
	v_max_f32_e32 v74, 0, v74
	v_rcp_f32_e32 v75, v75
	ds_read_u16 v76, v104 offset:32
	v_mfma_f32_16x16x32_bf16 v[174:177], v[66:69], v[56:59], v[174:177]
	s_waitcnt lgkmcnt(0)
	v_lshlrev_b32_e32 v76, 16, v76
	v_sqrt_f32_e32 v74, v74
	s_nop 0
	v_mul_f32_e32 v74, v75, v74
	v_mul_f32_e32 v74, v74, v76
	v_cvt_pk_bf16_f32 v74, v74, s0
	ds_write_b16 v124, v74 offset:38176
	v_mfma_f32_16x16x32_bf16 v[74:77], v[70:73], v[8:11], 0
	v_mfma_f32_16x16x32_bf16 v[74:77], v[66:69], v[24:27], v[74:77]
	s_nop 7
	v_fma_f32 v74, v74, s67, v167
	v_exp_f32_e32 v74, v74
	s_nop 0
	v_add_f32_e32 v74, 1.0, v74
	v_rcp_f32_e32 v74, v74
	v_fma_f32 v105, v174, s67, v168
	v_exp_f32_e32 v105, v105
	v_mul_f32_e32 v74, v169, v74
	v_add_f32_e32 v105, 1.0, v105
	v_exp_f32_e32 v74, v74
	ds_write_b32 v114, v74 offset:33920
	v_fma_f32 v74, -v74, v74, 1.0
	v_max_f32_e32 v74, 0, v74
	v_rcp_f32_e32 v105, v105
	ds_read_u16 v107, v110 offset:64
	s_waitcnt lgkmcnt(0)
	v_lshlrev_b32_e32 v107, 16, v107
	v_sqrt_f32_e32 v74, v74
	s_nop 0
	v_mul_f32_e32 v74, v105, v74
	v_mul_f32_e32 v74, v74, v107
	v_cvt_pk_bf16_f32 v74, v74, s0
	ds_write_b16 v121, v74 offset:38208
	v_fma_f32 v74, v75, s67, v167
	v_exp_f32_e32 v74, v74
	s_nop 0
	v_add_f32_e32 v74, 1.0, v74
	v_rcp_f32_e32 v74, v74
	v_fma_f32 v75, v175, s67, v168
	v_exp_f32_e32 v75, v75
	v_mul_f32_e32 v74, v169, v74
	v_add_f32_e32 v75, 1.0, v75
	v_exp_f32_e32 v74, v74
	ds_write_b32 v116, v74 offset:33920
	v_fma_f32 v74, -v74, v74, 1.0
	v_max_f32_e32 v74, 0, v74
	v_rcp_f32_e32 v75, v75
	ds_read_u16 v105, v108 offset:64
	s_waitcnt lgkmcnt(0)
	v_lshlrev_b32_e32 v105, 16, v105
	v_sqrt_f32_e32 v74, v74
	s_nop 0
	v_mul_f32_e32 v74, v75, v74
	v_mul_f32_e32 v74, v74, v105
	v_cvt_pk_bf16_f32 v74, v74, s0
	ds_write_b16 v122, v74 offset:38208
	v_fma_f32 v74, v76, s67, v167
	v_exp_f32_e32 v74, v74
	s_nop 0
	v_add_f32_e32 v74, 1.0, v74
	v_rcp_f32_e32 v74, v74
	v_fma_f32 v75, v176, s67, v168
	v_exp_f32_e32 v75, v75
	v_mul_f32_e32 v74, v169, v74
	v_add_f32_e32 v75, 1.0, v75
	v_exp_f32_e32 v74, v74
	ds_write_b32 v118, v74 offset:33920
	v_fma_f32 v74, -v74, v74, 1.0
	v_max_f32_e32 v74, 0, v74
	v_rcp_f32_e32 v75, v75
	ds_read_u16 v76, v106 offset:64
	s_waitcnt lgkmcnt(0)
; __device__ __forceinline__ bf16_t f2bf(float f) { return (bf16_t)(cvt_pk_bf16(f, 0.f) & 0xffffu); }
; __device__ __forceinline__ float bf2f(bf16_t b) { return __uint_as_float(((unsigned)b) << 16); }
; __device__ __forceinline__ float sigmoidf_(float x) { return 1.0f / (1.0f + __expf(-x)); }
; __device__ __forceinline__ void wave_lds_fence() { asm volatile("s_waitcnt lgkmcnt(0)" ::: "memory"); __builtin_amdgcn_wave_barrier(); }
; template <bool FINAL>
; __device__ __forceinline__ void lru_item(const Ctx& C, int l, int item) {
;     ...
; #pragma unroll
;             for (int dt = 0; dt < 4; ++dt) {
;                 f32x4 Da = {0.f, 0.f, 0.f, 0.f}, Dx = {0.f, 0.f, 0.f, 0.f};
;                 Da = __builtin_amdgcn_mfma_f32_16x16x32_bf16(xa0, Bw[0][dt][0], Da, 0, 0, 0); Da = __builtin_amdgcn_mfma_f32_16x16x32_bf16(xa1, Bw[0][dt][1], Da, 0, 0, 0);
;                 Dx = __builtin_amdgcn_mfma_f32_16x16x32_bf16(xa0, Bw[1][dt][0], Dx, 0, 0, 0); Dx = __builtin_amdgcn_mfma_f32_16x16x32_bf16(xa1, Bw[1][dt][1], Dx, 0, 0, 0);
; #pragma unroll
;                 for (int r = 0; r < 4; ++r) { const int tloc = 4 * quad + r, d = 16 * dt + fr;
;                     const float rg = sigmoidf_(Da[r] + bav[dt]), ig = sigmoidf_(Dx[r] + bxv[dt]), la = -8.0f * rg * spv[dt], a = __expf(la);
;                     const float x = bf2f(xc[(16 * tt + tloc) * XCP + n * 64 + d]);
;                     Al[tloc * 68 + d] = a; Ul[tloc * 68 + d] = f2bf(sqrtf(fmaxf(1.0f - a * a, 0.f)) * ig * x); }
;             }
;             wave_lds_fence();
; #pragma unroll
;             for (int j = 0; j < 16; ++j) { const int tloc = z ? 15 - j : j;
;                 const float a = Al[tloc * 68 + lane], u = bf2f(Ul[tloc * 68 + lane]);
;                 h = fmaf(a, h, u); Ap *= a;
;                 if (FINAL) Hz[(16 * tt + tloc) * 256 + n * 64 + lane] = f2bf(h); }
	v_lshlrev_b32_e32 v76, 16, v76
	v_sqrt_f32_e32 v74, v74
	s_nop 0
	v_mul_f32_e32 v74, v75, v74
	v_mul_f32_e32 v74, v74, v76
	v_cvt_pk_bf16_f32 v74, v74, s0
	ds_write_b16 v123, v74 offset:38208
	v_fma_f32 v74, v77, s67, v167
	v_exp_f32_e32 v74, v74
	s_nop 0
	v_add_f32_e32 v74, 1.0, v74
	v_rcp_f32_e32 v74, v74
	v_fma_f32 v75, v177, s67, v168
	v_exp_f32_e32 v75, v75
	v_mul_f32_e32 v74, v169, v74
	v_add_f32_e32 v75, 1.0, v75
	v_exp_f32_e32 v74, v74
	ds_write_b32 v120, v74 offset:33920
	v_fma_f32 v74, -v74, v74, 1.0
	v_max_f32_e32 v74, 0, v74
	v_rcp_f32_e32 v75, v75
	ds_read_u16 v76, v104 offset:64
	s_waitcnt lgkmcnt(0)
	v_lshlrev_b32_e32 v76, 16, v76
	v_sqrt_f32_e32 v74, v74
	s_nop 0
	v_mul_f32_e32 v74, v75, v74
	v_mul_f32_e32 v74, v74, v76
	v_cvt_pk_bf16_f32 v74, v74, s0
	ds_write_b16 v124, v74 offset:38208
	v_mfma_f32_16x16x32_bf16 v[74:77], v[70:73], v[12:15], 0
	v_mfma_f32_16x16x32_bf16 v[74:77], v[66:69], v[28:31], v[74:77]
	v_mfma_f32_16x16x32_bf16 v[70:73], v[70:73], v[44:47], 0
	v_mfma_f32_16x16x32_bf16 v[66:69], v[66:69], v[60:63], v[70:73]
	s_waitcnt vmcnt(2)
	s_nop 5
	v_fma_f32 v70, v74, s67, v170
	v_exp_f32_e32 v70, v70
	s_waitcnt vmcnt(1)
	v_fma_f32 v66, v66, s67, v171
	v_exp_f32_e32 v66, v66
	v_add_f32_e32 v70, 1.0, v70
	v_add_f32_e32 v66, 1.0, v66
	v_fma_f32 v67, v67, s67, v171
	v_rcp_f32_e32 v70, v70
	s_nop 0
	v_mul_f32_e32 v70, v172, v70
	v_exp_f32_e32 v70, v70
	ds_write_b32 v114, v70 offset:33984
	v_fma_f32 v70, -v70, v70, 1.0
	v_max_f32_e32 v70, 0, v70
	v_rcp_f32_e32 v66, v66
	ds_read_u16 v71, v110 offset:96
	v_exp_f32_e32 v67, v67
	s_waitcnt lgkmcnt(0)
	v_lshlrev_b32_e32 v71, 16, v71
	v_add_f32_e32 v67, 1.0, v67
	v_sqrt_f32_e32 v70, v70
	s_nop 0
	v_mul_f32_e32 v66, v66, v70
	v_mul_f32_e32 v66, v66, v71
	v_cvt_pk_bf16_f32 v66, v66, s0
	ds_write_b16 v121, v66 offset:38240
	v_fma_f32 v66, v75, s67, v170
	v_exp_f32_e32 v66, v66
	s_nop 0
	v_add_f32_e32 v66, 1.0, v66
	v_rcp_f32_e32 v66, v66
	s_nop 0
	v_mul_f32_e32 v66, v172, v66
	v_exp_f32_e32 v66, v66
	ds_write_b32 v116, v66 offset:33984
	v_fma_f32 v66, -v66, v66, 1.0
	v_max_f32_e32 v66, 0, v66
	v_rcp_f32_e32 v67, v67
	ds_read_u16 v70, v108 offset:96
	s_waitcnt lgkmcnt(0)
	v_lshlrev_b32_e32 v70, 16, v70
	v_sqrt_f32_e32 v66, v66
	s_nop 0
	v_mul_f32_e32 v66, v67, v66
	v_mul_f32_e32 v66, v66, v70
	v_cvt_pk_bf16_f32 v66, v66, s0
	ds_write_b16 v122, v66 offset:38240
	v_fma_f32 v66, v76, s67, v170
	v_exp_f32_e32 v66, v66
	s_nop 0
	v_add_f32_e32 v66, 1.0, v66
	v_rcp_f32_e32 v66, v66
	v_fma_f32 v67, v68, s67, v171
	v_exp_f32_e32 v67, v67
	v_mul_f32_e32 v66, v172, v66
	v_add_f32_e32 v67, 1.0, v67
	v_exp_f32_e32 v66, v66
	ds_write_b32 v118, v66 offset:33984
	v_fma_f32 v66, -v66, v66, 1.0
	v_max_f32_e32 v66, 0, v66
	v_rcp_f32_e32 v67, v67
	ds_read_u16 v68, v106 offset:96
	s_waitcnt lgkmcnt(0)
	v_lshlrev_b32_e32 v68, 16, v68
	v_sqrt_f32_e32 v66, v66
	s_nop 0
	v_mul_f32_e32 v66, v67, v66
	v_mul_f32_e32 v66, v66, v68
	v_cvt_pk_bf16_f32 v66, v66, s0
	ds_write_b16 v123, v66 offset:38240
	v_fma_f32 v66, v77, s67, v170
	v_exp_f32_e32 v66, v66
	s_nop 0
	v_add_f32_e32 v66, 1.0, v66
	v_rcp_f32_e32 v66, v66
	v_fma_f32 v67, v69, s67, v171
	v_exp_f32_e32 v67, v67
	v_mul_f32_e32 v66, v172, v66
	v_add_f32_e32 v67, 1.0, v67
	v_exp_f32_e32 v66, v66
	ds_write_b32 v120, v66 offset:33984
	v_fma_f32 v66, -v66, v66, 1.0
	v_max_f32_e32 v66, 0, v66
	v_rcp_f32_e32 v67, v67
	ds_read_u16 v68, v104 offset:96
	s_waitcnt lgkmcnt(0)
	v_lshlrev_b32_e32 v68, 16, v68
	v_sqrt_f32_e32 v66, v66
	s_nop 0
	v_mul_f32_e32 v66, v67, v66
	v_mul_f32_e32 v66, v66, v68
	v_cvt_pk_bf16_f32 v66, v66, s0
	ds_write_b16 v124, v66 offset:38240
	s_waitcnt lgkmcnt(0)
	ds_read_b32 v67, v113 offset:33792
	ds_read_u16 v66, v125 offset:38144
	s_waitcnt lgkmcnt(0)
	v_lshlrev_b32_e32 v66, 16, v66
	s_waitcnt vmcnt(0)
	v_fmac_f32_e32 v66, v67, v173
	v_cvt_pk_bf16_f32 v67, v66, s0
	s_or_b32 s0, s52, s13
	v_lshl_add_u32 v68, s0, 9, v141
	ds_write_b16 v68, v67
	ds_read_b32 v68, v126 offset:33792
	ds_read_u16 v67, v147 offset:38144
	s_waitcnt lgkmcnt(0)
	v_lshlrev_b32_e32 v67, 16, v67
	v_fmac_f32_e32 v67, v68, v66
	v_cvt_pk_bf16_f32 v66, v67, s0
	s_or_b32 s0, s52, s14
	v_lshl_add_u32 v68, s0, 9, v141
	ds_write_b16 v68, v66
	ds_read_b32 v66, v127 offset:33792
	ds_read_u16 v68, v148 offset:38144
	s_waitcnt lgkmcnt(0)
; __device__ __forceinline__ bf16_t f2bf(float f) { return (bf16_t)(cvt_pk_bf16(f, 0.f) & 0xffffu); }
; __device__ __forceinline__ float bf2f(bf16_t b) { return __uint_as_float(((unsigned)b) << 16); }
; __device__ __forceinline__ void wave_lds_fence() { asm volatile("s_waitcnt lgkmcnt(0)" ::: "memory"); __builtin_amdgcn_wave_barrier(); }
; template <bool FINAL>
; __device__ __forceinline__ void lru_item(const Ctx& C, int l, int item) {
;     ...
;             for (int j = 0; j < 16; ++j) { const int tloc = z ? 15 - j : j;
;                 const float a = Al[tloc * 68 + lane], u = bf2f(Ul[tloc * 68 + lane]);
;                 h = fmaf(a, h, u); Ap *= a;
;                 if (FINAL) Hz[(16 * tt + tloc) * 256 + n * 64 + lane] = f2bf(h); }
;             wave_lds_fence();
	v_lshlrev_b32_e32 v68, 16, v68
	v_fmac_f32_e32 v68, v66, v67
	v_cvt_pk_bf16_f32 v66, v68, s0
	s_or_b32 s0, s52, s15
	v_lshl_add_u32 v67, s0, 9, v141
	ds_write_b16 v67, v66
	ds_read_b32 v66, v128 offset:33792
	ds_read_u16 v67, v149 offset:38144
	s_waitcnt lgkmcnt(0)
	v_lshlrev_b32_e32 v67, 16, v67
	v_fmac_f32_e32 v67, v66, v68
	v_cvt_pk_bf16_f32 v66, v67, s0
	s_or_b32 s0, s52, s16
	v_lshl_add_u32 v68, s0, 9, v141
	ds_write_b16 v68, v66
	ds_read_b32 v66, v129 offset:33792
	ds_read_u16 v68, v150 offset:38144
	s_waitcnt lgkmcnt(0)
	v_lshlrev_b32_e32 v68, 16, v68
	v_fmac_f32_e32 v68, v66, v67
	v_cvt_pk_bf16_f32 v66, v68, s0
	s_or_b32 s0, s52, s17
	v_lshl_add_u32 v67, s0, 9, v141
	ds_write_b16 v67, v66
	ds_read_b32 v66, v130 offset:33792
	ds_read_u16 v67, v151 offset:38144
	s_waitcnt lgkmcnt(0)
	v_lshlrev_b32_e32 v67, 16, v67
	v_fmac_f32_e32 v67, v66, v68
	v_cvt_pk_bf16_f32 v66, v67, s0
	s_or_b32 s0, s52, s18
	v_lshl_add_u32 v68, s0, 9, v141
	ds_write_b16 v68, v66
	ds_read_b32 v66, v131 offset:33792
	ds_read_u16 v68, v152 offset:38144
	s_waitcnt lgkmcnt(0)
	v_lshlrev_b32_e32 v68, 16, v68
	v_fmac_f32_e32 v68, v66, v67
	v_cvt_pk_bf16_f32 v66, v68, s0
	s_or_b32 s0, s52, s19
	v_lshl_add_u32 v67, s0, 9, v141
	ds_write_b16 v67, v66
	ds_read_b32 v66, v132 offset:33792
	ds_read_u16 v67, v153 offset:38144
	s_waitcnt lgkmcnt(0)
	v_lshlrev_b32_e32 v67, 16, v67
	v_fmac_f32_e32 v67, v66, v68
	v_cvt_pk_bf16_f32 v66, v67, s0
	s_or_b32 s0, s52, s20
	v_lshl_add_u32 v68, s0, 9, v141
	ds_write_b16 v68, v66
	ds_read_b32 v66, v133 offset:33792
	ds_read_u16 v68, v154 offset:38144
	s_waitcnt lgkmcnt(0)
	v_lshlrev_b32_e32 v68, 16, v68
	v_fmac_f32_e32 v68, v66, v67
	v_cvt_pk_bf16_f32 v66, v68, s0
	s_or_b32 s0, s52, s21
	v_lshl_add_u32 v67, s0, 9, v141
	ds_write_b16 v67, v66
	ds_read_b32 v66, v134 offset:33792
	ds_read_u16 v67, v155 offset:38144
	s_waitcnt lgkmcnt(0)
	v_lshlrev_b32_e32 v67, 16, v67
	v_fmac_f32_e32 v67, v66, v68
	v_cvt_pk_bf16_f32 v66, v67, s0
	s_or_b32 s0, s52, s36
	v_lshl_add_u32 v68, s0, 9, v141
	ds_write_b16 v68, v66
	ds_read_b32 v66, v135 offset:33792
	ds_read_u16 v68, v156 offset:38144
	s_waitcnt lgkmcnt(0)
	v_lshlrev_b32_e32 v68, 16, v68
	v_fmac_f32_e32 v68, v66, v67
	v_cvt_pk_bf16_f32 v66, v68, s0
	s_or_b32 s0, s52, s38
	v_lshl_add_u32 v67, s0, 9, v141
	ds_write_b16 v67, v66
	ds_read_b32 v66, v136 offset:33792
	ds_read_u16 v67, v157 offset:38144
	s_waitcnt lgkmcnt(0)
	v_lshlrev_b32_e32 v67, 16, v67
	v_fmac_f32_e32 v67, v66, v68
	v_cvt_pk_bf16_f32 v66, v67, s0
	s_or_b32 s0, s52, s39
	v_lshl_add_u32 v68, s0, 9, v141
	ds_write_b16 v68, v66
	ds_read_b32 v66, v137 offset:33792
	ds_read_u16 v68, v158 offset:38144
	s_waitcnt lgkmcnt(0)
	v_lshlrev_b32_e32 v68, 16, v68
	v_fmac_f32_e32 v68, v66, v67
	v_cvt_pk_bf16_f32 v66, v68, s0
	s_or_b32 s0, s52, s42
	v_lshl_add_u32 v67, s0, 9, v141
	ds_write_b16 v67, v66
	ds_read_b32 v66, v138 offset:33792
	ds_read_u16 v67, v159 offset:38144
	s_waitcnt lgkmcnt(0)
	v_lshlrev_b32_e32 v67, 16, v67
	v_fmac_f32_e32 v67, v66, v68
	v_cvt_pk_bf16_f32 v66, v67, s0
	s_or_b32 s0, s52, s43
	v_lshl_add_u32 v68, s0, 9, v141
	ds_write_b16 v68, v66
	ds_read_b32 v68, v139 offset:33792
	ds_read_u16 v66, v160 offset:38144
	s_waitcnt lgkmcnt(0)
	v_lshlrev_b32_e32 v66, 16, v66
	v_fmac_f32_e32 v66, v68, v67
	v_cvt_pk_bf16_f32 v67, v66, s0
	s_or_b32 s0, s52, s44
	v_lshl_add_u32 v68, s0, 9, v141
	ds_write_b16 v68, v67
	ds_read_b32 v67, v140 offset:33792
	ds_read_u16 v68, v161 offset:38144
	s_waitcnt lgkmcnt(0)
	v_lshlrev_b32_e32 v173, 16, v68
	v_fmac_f32_e32 v173, v67, v66
	v_cvt_pk_bf16_f32 v66, v173, s0
	s_or_b32 s0, s52, s45
	v_lshl_add_u32 v67, s0, 9, v141
	ds_write_b16 v67, v66
	s_waitcnt lgkmcnt(0)
	s_cmp_eq_u32 s9, 4
	s_cbranch_scc0 .LBB0_681
	s_add_i32 s0, s8, s49
	s_ashr_i32 s1, s0, 31
	v_mov_b32_e32 v4, v99
	s_lshl_b64 s[8:9], s[0:1], 10
	s_lshl_b64 s[0:1], s[0:1], 9
	s_waitcnt lgkmcnt(0)
	s_barrier
	v_lshl_add_u64 v[0:1], v[100:101], 0, s[8:9]
	v_ashrrev_i32_e32 v5, 31, v4
	v_lshl_add_u64 v[2:3], v[102:103], 0, s[0:1]
	v_lshl_add_u32 v8, v4, 1, v143
	v_lshlrev_b64 v[4:5], 1, v[4:5]
	s_mov_b32 s0, 0
